# attention main loop: s_setprio 1 from the LDS-publish barrier to the back edge (compute segment outranks the co-resident workgroup's staging), s_setprio 0 before the branch; on top of v41
# speedup vs baseline: 1.0216x; 1.0216x over previous
; __device__ __forceinline__ f32x4 mfma16(bf16x8 a, bf16x8 b, f32x4 c) { return __builtin_amdgcn_mfma_f32_16x16x32_bf16(a, b, c, 0, 0, 0); }
; __device__ __forceinline__ void attn_item(CParams& p, int j2, int b, int h, int q0row, int nkeys, bf16_t* smem) {
;     ...
;         lds_sync();
; #pragma unroll
;         for (int i = 0; i < 2; ++i) {
;             *(u32x4*)(sK + (srow + i * 32) * GST + skc) = rk[i];
;             *(u32x4*)(sV + (srow + i * 32) * GST + skc) = rv[i];
;         }
;         lds_sync();
;         {
;             const int t0 = (kt + 1 < nt ? kt + 1 : kt) << 6;
; #pragma unroll
;             for (int i = 0; i < 2; ++i) {
;                 rk[i] = *(const u32x4*)(Kb + (size_t)(t0 + srow + i * 32) * 128 + skc);
;                 rv[i] = *(const u32x4*)(Vb + (size_t)(srow + i * 32) * TALL + t0 + skc);
;             }
;         }
;         bf16x8 pf[2][4];
; #pragma unroll
;         for (int ih = 0; ih < 2; ++ih) {
;             f32x4 s[4][2];
; #pragma unroll
;             for (int tt = 0; tt < 4; ++tt)
; #pragma unroll
;                 for (int i = 0; i < 2; ++i) s[tt][i] = (f32x4){-mb, -mb, -mb, -mb};
; #pragma unroll
;             for (int ks = 0; ks < 2; ++ks)
; #pragma unroll
;                 for (int tt = 0; tt < 4; ++tt) {
;                     const bf16x8 kf = lds16(sK + (tt * 16 + l16) * GST + ks * 32 + quad * 8);
; #pragma unroll
;                     for (int i = 0; i < 2; ++i) s[tt][i] = mfma16(kf, qf[ih * 2 + i][ks], s[tt][i]);
;                 }
; #pragma unroll
;             for (int i = 0; i < 2; ++i) {
; #pragma unroll
;                 for (int tt = 0; tt < 4; ++tt) {
; #pragma unroll
;                     for (int r = 0; r < 4; ++r) s[tt][i][r] = __builtin_amdgcn_exp2f(s[tt][i][r]);
;                 }
; #pragma unroll
;                 for (int ksp = 0; ksp < 2; ++ksp) pf[ksp][ih * 2 + i] = pack8(s[2 * ksp][i], s[2 * ksp + 1][i]);
;             }
;         }
.LBB0_179:
	s_add_i32 s4, s9, 1
	s_waitcnt lgkmcnt(0)
	s_barrier
	s_cmpk_lt_u32 s9, 0x83
	s_cselect_b32 s5, s4, s9
	s_lshl_b32 s6, s5, 6
	v_add_u32_e32 v188, s6, v176
	s_ashr_i32 s7, s6, 31
	v_add_u32_e32 v186, 32, v188
	v_lshl_add_u64 v[190:191], s[6:7], 1, v[180:181]
	v_ashrrev_i32_e32 v189, 31, v188
	v_ashrrev_i32_e32 v187, 31, v186
	s_cmpk_lg_i32 s4, 0x84
	s_mov_b32 s9, s4
	s_waitcnt vmcnt(3)
	ds_write_b128 v164, v[222:225]
	s_waitcnt vmcnt(2)
	ds_write_b128 v164, v[226:229] offset:9216
	s_waitcnt vmcnt(1)
	ds_write_b128 v164, v[230:233] offset:4608
	s_waitcnt vmcnt(0)
	ds_write_b128 v164, v[234:237] offset:13824
	s_waitcnt lgkmcnt(0)
	s_barrier
	s_setprio 1
	ds_read_b128 v[148:151], v171 offset:4608
	ds_read_b128 v[156:159], v171 offset:4672
	ds_read_b128 v[136:139], v171
	ds_read_b128 v[132:135], v171 offset:64
	s_waitcnt lgkmcnt(3)
	v_mfma_f32_16x16x32_bf16 v[160:163], v[148:151], v[4:7], v[44:47]
	ds_read_b128 v[152:155], v171 offset:6912
	ds_read_b128 v[140:143], v171 offset:2304
	ds_read_b128 v[144:147], v171 offset:2368
	s_waitcnt lgkmcnt(5)
	v_mfma_f32_16x16x32_bf16 v[234:237], v[156:159], v[8:11], v[160:163]
	s_nop 2
	ds_read_b128 v[160:163], v171 offset:6976
	s_waitcnt lgkmcnt(5)
	v_mfma_f32_16x16x32_bf16 v[116:119], v[136:139], v[4:7], v[44:47]
	s_nop 1
	v_exp_f32_e32 v234, v234
	v_exp_f32_e32 v235, v235
	v_exp_f32_e32 v236, v236
	s_waitcnt lgkmcnt(3)
	v_mfma_f32_16x16x32_bf16 v[226:229], v[152:155], v[4:7], v[44:47]
	v_exp_f32_e32 v237, v237
	v_mfma_f32_16x16x32_bf16 v[120:123], v[136:139], v[12:15], v[44:47]
	s_waitcnt lgkmcnt(2)
	v_mfma_f32_16x16x32_bf16 v[124:127], v[140:143], v[4:7], v[44:47]
	v_mfma_f32_16x16x32_bf16 v[222:225], v[148:151], v[12:15], v[44:47]
	v_mfma_f32_16x16x32_bf16 v[230:233], v[152:155], v[12:15], v[44:47]
	v_mfma_f32_16x16x32_bf16 v[116:119], v[132:135], v[8:11], v[116:119]
	s_waitcnt lgkmcnt(0)
	v_mfma_f32_16x16x32_bf16 v[226:229], v[160:163], v[8:11], v[226:229]
	v_mfma_f32_16x16x32_bf16 v[128:131], v[140:143], v[12:15], v[44:47]
	s_nop 4
	v_exp_f32_e32 v118, v118
	v_exp_f32_e32 v119, v119
	v_exp_f32_e32 v226, v226
	v_mfma_f32_16x16x32_bf16 v[120:123], v[132:135], v[24:27], v[120:123]
	v_exp_f32_e32 v227, v227
	v_exp_f32_e32 v228, v228
	v_exp_f32_e32 v229, v229
	v_mfma_f32_16x16x32_bf16 v[124:127], v[144:147], v[8:11], v[124:127]
	v_exp_f32_e32 v116, v116
	v_exp_f32_e32 v117, v117
	s_nop 1
	v_exp_f32_e32 v120, v120
	v_mfma_f32_16x16x32_bf16 v[222:225], v[156:159], v[24:27], v[222:225]
	v_exp_f32_e32 v121, v121
	s_nop 0
	v_exp_f32_e32 v175, v124
	v_exp_f32_e32 v177, v125
	v_mfma_f32_16x16x32_bf16 v[230:233], v[160:163], v[24:27], v[230:233]
	v_cvt_pk_bf16_f32 v125, v118, v119
	v_cvt_pk_bf16_f32 v118, v226, v227
	v_cvt_pk_bf16_f32 v119, v228, v229
	v_mfma_f32_16x16x32_bf16 v[128:131], v[144:147], v[24:27], v[128:131]
	v_exp_f32_e32 v122, v122
	v_exp_f32_e32 v123, v123
	v_exp_f32_e32 v222, v222
	v_exp_f32_e32 v223, v223
	v_exp_f32_e32 v224, v224
	v_exp_f32_e32 v225, v225
	v_exp_f32_e32 v226, v230
	v_exp_f32_e32 v227, v231
	v_exp_f32_e32 v228, v232
	v_exp_f32_e32 v229, v233
	v_exp_f32_e32 v221, v126
	v_cvt_pk_bf16_f32 v124, v116, v117
	v_cvt_pk_bf16_f32 v126, v175, v177
	v_cvt_pk_bf16_f32 v116, v234, v235
	v_cvt_pk_bf16_f32 v117, v236, v237
	v_exp_f32_e32 v175, v128
	v_exp_f32_e32 v177, v129
	v_cvt_pk_bf16_f32 v128, v120, v121
	v_cvt_pk_bf16_f32 v129, v122, v123
	v_cvt_pk_bf16_f32 v120, v222, v223
	v_cvt_pk_bf16_f32 v121, v224, v225
	v_cvt_pk_bf16_f32 v122, v226, v227
	v_cvt_pk_bf16_f32 v123, v228, v229
	v_mfma_f32_16x16x32_bf16 v[222:225], v[136:139], v[28:31], v[44:47]
	v_exp_f32_e32 v127, v127
	v_exp_f32_e32 v131, v131
	v_cvt_pk_bf16_f32 v127, v221, v127
	v_mfma_f32_16x16x32_bf16 v[136:139], v[136:139], v[36:39], v[44:47]
	v_exp_f32_e32 v221, v130
	v_cvt_pk_bf16_f32 v130, v175, v177
	v_cvt_pk_bf16_f32 v131, v221, v131
	v_mfma_f32_16x16x32_bf16 v[226:229], v[140:143], v[28:31], v[44:47]
	v_mfma_f32_16x16x32_bf16 v[140:143], v[140:143], v[36:39], v[44:47]
	v_mfma_f32_16x16x32_bf16 v[230:233], v[148:151], v[28:31], v[44:47]
	v_mfma_f32_16x16x32_bf16 v[148:151], v[148:151], v[36:39], v[44:47]
	v_mfma_f32_16x16x32_bf16 v[234:237], v[152:155], v[28:31], v[44:47]
	v_mfma_f32_16x16x32_bf16 v[152:155], v[152:155], v[36:39], v[44:47]
	v_mfma_f32_16x16x32_bf16 v[222:225], v[132:135], v[32:35], v[222:225]
	v_mfma_f32_16x16x32_bf16 v[136:139], v[132:135], v[40:43], v[136:139]
	v_mfma_f32_16x16x32_bf16 v[132:135], v[144:147], v[32:35], v[226:229]
	v_mfma_f32_16x16x32_bf16 v[144:147], v[144:147], v[40:43], v[140:143]
	s_nop 5
	v_exp_f32_e32 v138, v138
	v_exp_f32_e32 v134, v134
	v_exp_f32_e32 v135, v135
	v_mfma_f32_16x16x32_bf16 v[140:143], v[156:159], v[32:35], v[230:233]
	v_exp_f32_e32 v139, v139
	v_exp_f32_e32 v136, v136
	v_exp_f32_e32 v137, v137
	v_mfma_f32_16x16x32_bf16 v[148:151], v[156:159], v[40:43], v[148:151]
	v_exp_f32_e32 v132, v132
	v_exp_f32_e32 v133, v133
	v_exp_f32_e32 v147, v147
	v_mfma_f32_16x16x32_bf16 v[156:159], v[160:163], v[32:35], v[234:237]
	v_exp_f32_e32 v175, v140
	s_nop 2
	v_exp_f32_e32 v148, v148
	v_exp_f32_e32 v149, v149
	v_mfma_f32_16x16x32_bf16 v[152:155], v[160:163], v[40:43], v[152:155]
	v_exp_f32_e32 v150, v150
	v_exp_f32_e32 v156, v156
	v_exp_f32_e32 v157, v157
	v_exp_f32_e32 v151, v151
	v_exp_f32_e32 v160, v222
	s_nop 2
	v_exp_f32_e32 v154, v154
	v_exp_f32_e32 v155, v155
	v_exp_f32_e32 v222, v143
	v_cvt_pk_bf16_f32 v143, v134, v135
	v_cvt_pk_bf16_f32 v134, v156, v157
	v_exp_f32_e32 v157, v145
	v_cvt_pk_bf16_f32 v145, v138, v139
	v_cvt_pk_bf16_f32 v139, v154, v155
	v_add_u32_e32 v154, 0x2000, v173
	v_exp_f32_e32 v158, v158
	v_exp_f32_e32 v159, v159
	v_exp_f32_e32 v156, v144
; __device__ __forceinline__ f32x4 mfma16(bf16x8 a, bf16x8 b, f32x4 c) { return __builtin_amdgcn_mfma_f32_16x16x32_bf16(a, b, c, 0, 0, 0); }
; __device__ __forceinline__ void attn_item(CParams& p, int j2, int b, int h, int q0row, int nkeys, bf16_t* smem) {
;     ...
;             const int t0 = (kt + 1 < nt ? kt + 1 : kt) << 6;
; #pragma unroll
;             for (int i = 0; i < 2; ++i) {
;                 rk[i] = *(const u32x4*)(Kb + (size_t)(t0 + srow + i * 32) * 128 + skc);
;                 rv[i] = *(const u32x4*)(Vb + (size_t)(srow + i * 32) * TALL + t0 + skc);
;             }
;         }
;         bf16x8 pf[2][4];
; #pragma unroll
;         for (int ih = 0; ih < 2; ++ih) {
;             f32x4 s[4][2];
; #pragma unroll
;             for (int tt = 0; tt < 4; ++tt)
; #pragma unroll
;                 for (int i = 0; i < 2; ++i) s[tt][i] = (f32x4){-mb, -mb, -mb, -mb};
; #pragma unroll
;             for (int ks = 0; ks < 2; ++ks)
; #pragma unroll
;                 for (int tt = 0; tt < 4; ++tt) {
;                     const bf16x8 kf = lds16(sK + (tt * 16 + l16) * GST + ks * 32 + quad * 8);
; #pragma unroll
;                     for (int i = 0; i < 2; ++i) s[tt][i] = mfma16(kf, qf[ih * 2 + i][ks], s[tt][i]);
;                 }
; #pragma unroll
;             for (int i = 0; i < 2; ++i) {
; #pragma unroll
;                 for (int tt = 0; tt < 4; ++tt) {
; #pragma unroll
;                     for (int r = 0; r < 4; ++r) s[tt][i][r] = __builtin_amdgcn_exp2f(s[tt][i][r]);
;                 }
; #pragma unroll
;                 for (int ksp = 0; ksp < 2; ++ksp) pf[ksp][ih * 2 + i] = pack8(s[2 * ksp][i], s[2 * ksp + 1][i]);
;             }
;         }
; #pragma unroll
;         for (int ksp = 0; ksp < 2; ++ksp)
; #pragma unroll
;             for (int d = 0; d < 5; ++d) {
;                 const bf16_t* vp = sV + (d * 16 + l16) * GST + ksp * 32 + quad * 4;
;                 const bf16x8 vf = lds8x2(vp, vp + 16);
; #pragma unroll
;                 for (int i = 0; i < 4; ++i) o[d][i] = mfma16(vf, pf[ksp][i], o[d][i]);
;             }
	v_cvt_pk_bf16_f32 v144, v136, v137
	v_cvt_pk_bf16_f32 v136, v148, v149
	v_cvt_pk_bf16_f32 v137, v150, v151
	ds_read2_b64 v[148:151], v154 offset0:128 offset1:132
	v_exp_f32_e32 v161, v223
	v_exp_f32_e32 v162, v224
	v_exp_f32_e32 v163, v225
	v_cvt_pk_bf16_f32 v135, v158, v159
	v_exp_f32_e32 v158, v146
	v_exp_f32_e32 v152, v152
	v_exp_f32_e32 v153, v153
	v_exp_f32_e32 v177, v141
	v_exp_f32_e32 v221, v142
	v_cvt_pk_bf16_f32 v140, v160, v161
	v_cvt_pk_bf16_f32 v141, v162, v163
	v_cvt_pk_bf16_f32 v142, v132, v133
	v_cvt_pk_bf16_f32 v146, v156, v157
	v_cvt_pk_bf16_f32 v147, v158, v147
	v_cvt_pk_bf16_f32 v138, v152, v153
	v_cvt_pk_bf16_f32 v132, v175, v177
	v_cvt_pk_bf16_f32 v133, v221, v222
	v_add_u32_e32 v152, 0x2800, v173
	v_add_u32_e32 v153, 0x3000, v173
	ds_read2_b64 v[160:163], v152 offset0:160 offset1:164
	v_add_u32_e32 v155, 0x3800, v173
	ds_read2_b64 v[156:159], v153 offset0:192 offset1:196
	v_add_u32_e32 v175, 0x4800, v173
	v_lshlrev_b64 v[222:223], 8, v[188:189]
	v_lshl_add_u64 v[222:223], v[178:179], 0, v[222:223]
	v_lshl_add_u64 v[226:227], v[190:191], 0, v[182:183]
	global_load_dwordx4 v[222:225], v[222:223], off
	v_lshlrev_b64 v[230:231], 8, v[186:187]
	global_load_dwordx4 v[226:229], v[226:227], off
	v_lshl_add_u64 v[230:231], v[178:179], 0, v[230:231]
	v_lshl_add_u64 v[234:235], v[190:191], 0, v[184:185]
	global_load_dwordx4 v[230:233], v[230:231], off
	global_load_dwordx4 v[234:237], v[234:235], off
	s_waitcnt lgkmcnt(2)
	v_mfma_f32_16x16x32_bf16 v[112:115], v[148:151], v[124:127], v[112:115]
	v_mfma_f32_16x16x32_bf16 v[108:111], v[148:151], v[128:131], v[108:111]
	v_mfma_f32_16x16x32_bf16 v[100:103], v[148:151], v[140:143], v[100:103]
	v_mfma_f32_16x16x32_bf16 v[80:83], v[148:151], v[144:147], v[80:83]
	ds_read2_b64 v[148:151], v155 offset0:224 offset1:228
	s_waitcnt lgkmcnt(2)
	v_mfma_f32_16x16x32_bf16 v[96:99], v[160:163], v[124:127], v[96:99]
	v_mfma_f32_16x16x32_bf16 v[76:79], v[160:163], v[128:131], v[76:79]
	v_mfma_f32_16x16x32_bf16 v[60:63], v[160:163], v[140:143], v[60:63]
	v_mfma_f32_16x16x32_bf16 v[20:23], v[160:163], v[144:147], v[20:23]
	ds_read2_b64 v[160:163], v175 offset1:4
	s_waitcnt lgkmcnt(2)
	v_mfma_f32_16x16x32_bf16 v[88:91], v[156:159], v[124:127], v[88:91]
	v_mfma_f32_16x16x32_bf16 v[68:71], v[156:159], v[128:131], v[68:71]
	v_mfma_f32_16x16x32_bf16 v[52:55], v[156:159], v[140:143], v[52:55]
	v_mfma_f32_16x16x32_bf16 v[0:3], v[156:159], v[144:147], v[0:3]
	ds_read2_b64 v[156:159], v154 offset0:136 offset1:140
	s_waitcnt lgkmcnt(2)
	v_mfma_f32_16x16x32_bf16 v[92:95], v[148:151], v[124:127], v[92:95]
	v_mfma_f32_16x16x32_bf16 v[72:75], v[148:151], v[128:131], v[72:75]
	v_mfma_f32_16x16x32_bf16 v[56:59], v[148:151], v[140:143], v[56:59]
	v_mfma_f32_16x16x32_bf16 v[16:19], v[148:151], v[144:147], v[16:19]
	ds_read2_b64 v[148:151], v152 offset0:168 offset1:172
	s_waitcnt lgkmcnt(2)
	v_mfma_f32_16x16x32_bf16 v[104:107], v[160:163], v[124:127], v[104:107]
	v_mfma_f32_16x16x32_bf16 v[84:87], v[160:163], v[128:131], v[84:87]
	v_mfma_f32_16x16x32_bf16 v[64:67], v[160:163], v[140:143], v[64:67]
	v_mfma_f32_16x16x32_bf16 v[48:51], v[160:163], v[144:147], v[48:51]
	ds_read2_b64 v[160:163], v153 offset0:200 offset1:204
	s_waitcnt lgkmcnt(2)
	v_mfma_f32_16x16x32_bf16 v[112:115], v[156:159], v[116:119], v[112:115]
	v_mfma_f32_16x16x32_bf16 v[108:111], v[156:159], v[120:123], v[108:111]
	v_mfma_f32_16x16x32_bf16 v[100:103], v[156:159], v[132:135], v[100:103]
	v_mfma_f32_16x16x32_bf16 v[80:83], v[156:159], v[136:139], v[80:83]
	ds_read2_b64 v[156:159], v155 offset0:232 offset1:236
	s_waitcnt lgkmcnt(2)
	v_mfma_f32_16x16x32_bf16 v[96:99], v[148:151], v[116:119], v[96:99]
	v_mfma_f32_16x16x32_bf16 v[76:79], v[148:151], v[120:123], v[76:79]
	v_mfma_f32_16x16x32_bf16 v[60:63], v[148:151], v[132:135], v[60:63]
	v_mfma_f32_16x16x32_bf16 v[20:23], v[148:151], v[136:139], v[20:23]
	ds_read2_b64 v[148:151], v175 offset0:8 offset1:12
	s_waitcnt lgkmcnt(2)
	v_mfma_f32_16x16x32_bf16 v[88:91], v[160:163], v[116:119], v[88:91]
	v_mfma_f32_16x16x32_bf16 v[68:71], v[160:163], v[120:123], v[68:71]
	v_mfma_f32_16x16x32_bf16 v[52:55], v[160:163], v[132:135], v[52:55]
	v_mfma_f32_16x16x32_bf16 v[0:3], v[160:163], v[136:139], v[0:3]
	s_waitcnt lgkmcnt(1)
	v_mfma_f32_16x16x32_bf16 v[92:95], v[156:159], v[116:119], v[92:95]
	v_mfma_f32_16x16x32_bf16 v[72:75], v[156:159], v[120:123], v[72:75]
	v_mfma_f32_16x16x32_bf16 v[56:59], v[156:159], v[132:135], v[56:59]
	v_mfma_f32_16x16x32_bf16 v[16:19], v[156:159], v[136:139], v[16:19]
	s_waitcnt lgkmcnt(0)
	v_mfma_f32_16x16x32_bf16 v[104:107], v[148:151], v[116:119], v[104:107]
	v_mfma_f32_16x16x32_bf16 v[84:87], v[148:151], v[120:123], v[84:87]
	v_mfma_f32_16x16x32_bf16 v[64:67], v[148:151], v[132:135], v[64:67]
	v_mfma_f32_16x16x32_bf16 v[48:51], v[148:151], v[136:139], v[48:51]
	s_setprio 0
	s_cbranch_scc1 .LBB0_179
; __device__ __forceinline__ void attn_item(CParams& p, int j2, int b, int h, int q0row, int nkeys, bf16_t* smem) {
;     ...
;     bf16_t* as = (bf16_t*)(p.ws + WS_AS);
; #pragma unroll
;     for (int i = 0; i < 4; ++i) {
;         const float l = __shfl(o[4][i][0], l16);
;         const float inv = 1.f / l;
;         const int row = q0row + wave * 64 + i * 16 + l16;
; #pragma unroll
;         for (int d = 0; d < 4; ++d)
;             st4bf(as + frag_off(row, h * 64 + d * 16 + quad * 4, 1024), o[d][i][0] * inv, o[d][i][1] * inv, o[d][i][2] * inv, o[d][i][3] * inv);
;     }
	s_waitcnt vmcnt(0)
	v_and_or_b32 v4, v197, 64, v220
	v_lshlrev_b32_e32 v14, 2, v4
	s_nop 1
	ds_bpermute_b32 v4, v14, v104
	v_and_or_b32 v7, v169, 16, v220
	s_lshl_b32 s78, s8, 11
	v_lshlrev_b32_e32 v164, 4, v7
	s_mov_b32 s39, s0
	s_waitcnt lgkmcnt(0)
	v_div_scale_f32 v5, s[4:5], v4, v4, 1.0
	v_rcp_f32_e32 v6, v5
	s_nop 0
	v_fma_f32 v8, -v5, v6, 1.0
	v_fmac_f32_e32 v6, v8, v6
	v_div_scale_f32 v8, vcc, 1.0, v4, 1.0
	v_mul_f32_e32 v9, v8, v6
	v_fma_f32 v10, -v5, v9, v8
	v_fmac_f32_e32 v9, v10, v6
	v_fma_f32 v5, -v5, v9, v8
	v_div_fmas_f32 v5, v5, v6, v9
	v_div_fixup_f32 v6, v5, v4, 1.0
	v_ashrrev_i32_e32 v4, 4, v219
	v_ashrrev_i32_e32 v5, 31, v4
	v_lshlrev_b64 v[4:5], 15, v[4:5]
	v_lshl_add_u64 v[4:5], s[50:51], 0, v[4:5]
	v_lshl_add_u64 v[4:5], v[4:5], 0, s[78:79]
	v_lshl_add_u64 v[8:9], v[4:5], 0, v[164:165]
	v_and_b32_e32 v4, 8, v169
	v_mov_b32_e32 v5, v165
	v_pk_mul_f32 v[10:11], v[112:113], v[6:7] op_sel_hi:[1,0]
	v_pk_mul_f32 v[12:13], v[114:115], v[6:7] op_sel_hi:[1,0]
	v_lshl_add_u64 v[8:9], v[8:9], 0, v[4:5]
	v_cvt_pk_bf16_f32 v10, v10, v11
	v_cvt_pk_bf16_f32 v11, v12, v13
	global_store_dwordx2 v[8:9], v[10:11], off
	v_pk_mul_f32 v[10:11], v[96:97], v[6:7] op_sel_hi:[1,0]
	v_pk_mul_f32 v[12:13], v[98:99], v[6:7] op_sel_hi:[1,0]
	v_cvt_pk_bf16_f32 v10, v10, v11
	v_cvt_pk_bf16_f32 v11, v12, v13
	global_store_dwordx2 v[8:9], v[10:11], off offset:512
	v_pk_mul_f32 v[10:11], v[88:89], v[6:7] op_sel_hi:[1,0]
	v_pk_mul_f32 v[12:13], v[90:91], v[6:7] op_sel_hi:[1,0]
	v_cvt_pk_bf16_f32 v10, v10, v11
	v_cvt_pk_bf16_f32 v11, v12, v13
	global_store_dwordx2 v[8:9], v[10:11], off offset:1024
	v_pk_mul_f32 v[10:11], v[92:93], v[6:7] op_sel_hi:[1,0]
	v_pk_mul_f32 v[6:7], v[94:95], v[6:7] op_sel_hi:[1,0]
	v_cvt_pk_bf16_f32 v10, v10, v11
	v_cvt_pk_bf16_f32 v11, v6, v7
	ds_bpermute_b32 v6, v14, v84
	global_store_dwordx2 v[8:9], v[10:11], off offset:1536
	s_waitcnt lgkmcnt(0)
	v_div_scale_f32 v7, s[4:5], v6, v6, 1.0
	v_rcp_f32_e32 v8, v7
	s_nop 0
	v_fma_f32 v9, -v7, v8, 1.0
	v_fmac_f32_e32 v8, v9, v8
	v_div_scale_f32 v9, vcc, 1.0, v6, 1.0
	v_mul_f32_e32 v10, v9, v8
	v_fma_f32 v11, -v7, v10, v9
	v_fmac_f32_e32 v10, v11, v8
	v_fma_f32 v7, -v7, v10, v9
	v_div_fmas_f32 v7, v7, v8, v10
	v_ashrrev_i32_e32 v8, 4, v174
	v_ashrrev_i32_e32 v9, 31, v8
	v_lshlrev_b64 v[8:9], 15, v[8:9]
	v_lshl_add_u64 v[8:9], s[50:51], 0, v[8:9]
	v_div_fixup_f32 v6, v7, v6, 1.0
	v_lshl_add_u64 v[8:9], v[8:9], 0, s[78:79]
	v_lshl_add_u64 v[8:9], v[8:9], 0, v[164:165]
	v_pk_mul_f32 v[10:11], v[108:109], v[6:7] op_sel_hi:[1,0]
	v_pk_mul_f32 v[12:13], v[110:111], v[6:7] op_sel_hi:[1,0]
	v_lshl_add_u64 v[8:9], v[8:9], 0, v[4:5]
	v_cvt_pk_bf16_f32 v10, v10, v11
	v_cvt_pk_bf16_f32 v11, v12, v13
	global_store_dwordx2 v[8:9], v[10:11], off
	v_pk_mul_f32 v[10:11], v[76:77], v[6:7] op_sel_hi:[1,0]
	v_pk_mul_f32 v[12:13], v[78:79], v[6:7] op_sel_hi:[1,0]
	v_cvt_pk_bf16_f32 v10, v10, v11
	v_cvt_pk_bf16_f32 v11, v12, v13
	global_store_dwordx2 v[8:9], v[10:11], off offset:512
	v_pk_mul_f32 v[10:11], v[68:69], v[6:7] op_sel_hi:[1,0]
	v_pk_mul_f32 v[12:13], v[70:71], v[6:7] op_sel_hi:[1,0]
	v_cvt_pk_bf16_f32 v10, v10, v11
	v_cvt_pk_bf16_f32 v11, v12, v13
	global_store_dwordx2 v[8:9], v[10:11], off offset:1024
	v_pk_mul_f32 v[10:11], v[72:73], v[6:7] op_sel_hi:[1,0]
	v_pk_mul_f32 v[6:7], v[74:75], v[6:7] op_sel_hi:[1,0]
	v_cvt_pk_bf16_f32 v10, v10, v11
	v_cvt_pk_bf16_f32 v11, v6, v7
	ds_bpermute_b32 v6, v14, v64
	global_store_dwordx2 v[8:9], v[10:11], off offset:1536
	s_waitcnt lgkmcnt(0)
	v_div_scale_f32 v7, s[4:5], v6, v6, 1.0
	v_rcp_f32_e32 v8, v7
	s_nop 0
	v_fma_f32 v9, -v7, v8, 1.0
	v_fmac_f32_e32 v8, v9, v8
	v_div_scale_f32 v9, vcc, 1.0, v6, 1.0
	v_mul_f32_e32 v10, v9, v8
	v_fma_f32 v11, -v7, v10, v9
	v_fmac_f32_e32 v10, v11, v8
	v_fma_f32 v7, -v7, v10, v9
	v_div_fmas_f32 v7, v7, v8, v10
	v_ashrrev_i32_e32 v8, 4, v172
	v_ashrrev_i32_e32 v9, 31, v8
	v_lshlrev_b64 v[8:9], 15, v[8:9]
	v_lshl_add_u64 v[8:9], s[50:51], 0, v[8:9]
	v_div_fixup_f32 v6, v7, v6, 1.0
	v_lshl_add_u64 v[8:9], v[8:9], 0, s[78:79]
	v_lshl_add_u64 v[8:9], v[8:9], 0, v[164:165]
	v_pk_mul_f32 v[10:11], v[100:101], v[6:7] op_sel_hi:[1,0]
	v_pk_mul_f32 v[12:13], v[102:103], v[6:7] op_sel_hi:[1,0]
	v_lshl_add_u64 v[8:9], v[8:9], 0, v[4:5]
	v_cvt_pk_bf16_f32 v10, v10, v11
	v_cvt_pk_bf16_f32 v11, v12, v13
	global_store_dwordx2 v[8:9], v[10:11], off
	v_pk_mul_f32 v[10:11], v[60:61], v[6:7] op_sel_hi:[1,0]
	v_pk_mul_f32 v[12:13], v[62:63], v[6:7] op_sel_hi:[1,0]
	v_cvt_pk_bf16_f32 v10, v10, v11
	v_cvt_pk_bf16_f32 v11, v12, v13
	global_store_dwordx2 v[8:9], v[10:11], off offset:512
	v_pk_mul_f32 v[10:11], v[52:53], v[6:7] op_sel_hi:[1,0]
	v_pk_mul_f32 v[12:13], v[54:55], v[6:7] op_sel_hi:[1,0]
	v_cvt_pk_bf16_f32 v10, v10, v11
	v_cvt_pk_bf16_f32 v11, v12, v13
	global_store_dwordx2 v[8:9], v[10:11], off offset:1024
	v_pk_mul_f32 v[10:11], v[56:57], v[6:7] op_sel_hi:[1,0]
	v_pk_mul_f32 v[6:7], v[58:59], v[6:7] op_sel_hi:[1,0]
	v_cvt_pk_bf16_f32 v10, v10, v11
	v_cvt_pk_bf16_f32 v11, v6, v7
	ds_bpermute_b32 v6, v14, v48
	global_store_dwordx2 v[8:9], v[10:11], off offset:1536
	s_waitcnt lgkmcnt(0)
	v_div_scale_f32 v7, s[4:5], v6, v6, 1.0
	v_rcp_f32_e32 v8, v7
	s_nop 0
	v_fma_f32 v9, -v7, v8, 1.0
	v_fmac_f32_e32 v8, v9, v8
	v_div_scale_f32 v9, vcc, 1.0, v6, 1.0
	v_mul_f32_e32 v10, v9, v8
	v_fma_f32 v11, -v7, v10, v9
	v_fmac_f32_e32 v10, v11, v8
	v_fma_f32 v7, -v7, v10, v9
	v_div_fmas_f32 v7, v7, v8, v10
	v_ashrrev_i32_e32 v8, 4, v170
	v_ashrrev_i32_e32 v9, 31, v8
	v_lshlrev_b64 v[8:9], 15, v[8:9]
	v_lshl_add_u64 v[8:9], s[50:51], 0, v[8:9]
	v_lshl_add_u64 v[8:9], v[8:9], 0, s[78:79]
	v_div_fixup_f32 v6, v7, v6, 1.0
	v_lshl_add_u64 v[8:9], v[8:9], 0, v[164:165]
	v_lshl_add_u64 v[4:5], v[8:9], 0, v[4:5]
	v_pk_mul_f32 v[8:9], v[80:81], v[6:7] op_sel_hi:[1,0]
	v_pk_mul_f32 v[10:11], v[82:83], v[6:7] op_sel_hi:[1,0]
	v_pk_mul_f32 v[0:1], v[0:1], v[6:7] op_sel_hi:[1,0]
	v_pk_mul_f32 v[2:3], v[2:3], v[6:7] op_sel_hi:[1,0]
	v_cvt_pk_bf16_f32 v8, v8, v9
	v_cvt_pk_bf16_f32 v9, v10, v11
	v_cvt_pk_bf16_f32 v0, v0, v1
	v_cvt_pk_bf16_f32 v1, v2, v3
	global_store_dwordx2 v[4:5], v[8:9], off
	v_pk_mul_f32 v[8:9], v[20:21], v[6:7] op_sel_hi:[1,0]
	v_pk_mul_f32 v[10:11], v[22:23], v[6:7] op_sel_hi:[1,0]
	global_store_dwordx2 v[4:5], v[0:1], off offset:1024
	v_pk_mul_f32 v[0:1], v[16:17], v[6:7] op_sel_hi:[1,0]
	v_pk_mul_f32 v[2:3], v[18:19], v[6:7] op_sel_hi:[1,0]
	v_cvt_pk_bf16_f32 v8, v8, v9
	v_cvt_pk_bf16_f32 v9, v10, v11
	v_cvt_pk_bf16_f32 v0, v0, v1
	v_cvt_pk_bf16_f32 v1, v2, v3
	global_store_dwordx2 v[4:5], v[8:9], off offset:512
	global_store_dwordx2 v[4:5], v[0:1], off offset:1536
	s_branch .LBB0_166
